# phase-1 compress-bias dot product: 4 load batches in flight (same loads, same fp32 fmac order), position values loaded as dwordx4
# baseline (speedup 1.0000x reference)
.LBB0_277:
	s_mov_b64 s[8:9], 0x1000
	global_load_dwordx4 v[22:25], v[0:1], off
	global_load_dwordx4 v[26:29], v[0:1], off offset:16
	global_load_dwordx4 v[30:33], v[0:1], off offset:32
	global_load_dwordx4 v[34:37], v[0:1], off offset:48
	global_load_dword v38, v[2:3], off
	global_load_dword v39, v[2:3], off offset:1024
	global_load_dword v40, v[2:3], off offset:2048
	global_load_dword v41, v[2:3], off offset:3072
	v_lshl_add_u64 v[2:3], v[2:3], 0, s[8:9]
	global_load_dword v42, v[2:3], off
	global_load_dword v43, v[2:3], off offset:1024
	global_load_dword v44, v[2:3], off offset:2048
	global_load_dword v45, v[2:3], off offset:3072
	v_lshl_add_u64 v[2:3], v[2:3], 0, s[8:9]
	global_load_dword v46, v[2:3], off
	global_load_dword v47, v[2:3], off offset:1024
	global_load_dword v48, v[2:3], off offset:2048
	global_load_dword v49, v[2:3], off offset:3072
	v_lshl_add_u64 v[2:3], v[2:3], 0, s[8:9]
	global_load_dword v50, v[2:3], off
	global_load_dword v51, v[2:3], off offset:1024
	global_load_dword v52, v[2:3], off offset:2048
	global_load_dword v53, v[2:3], off offset:3072
	v_lshl_add_u64 v[2:3], v[2:3], 0, s[8:9]
	global_load_dwordx4 v[84:87], v[0:1], off offset:64
	global_load_dwordx4 v[88:91], v[0:1], off offset:80
	global_load_dwordx4 v[92:95], v[0:1], off offset:96
	global_load_dwordx4 v[96:99], v[0:1], off offset:112
	global_load_dword v100, v[2:3], off
	global_load_dword v101, v[2:3], off offset:1024
	global_load_dword v102, v[2:3], off offset:2048
	global_load_dword v103, v[2:3], off offset:3072
	v_lshl_add_u64 v[2:3], v[2:3], 0, s[8:9]
	global_load_dword v104, v[2:3], off
	global_load_dword v105, v[2:3], off offset:1024
	global_load_dword v106, v[2:3], off offset:2048
	global_load_dword v107, v[2:3], off offset:3072
	v_lshl_add_u64 v[2:3], v[2:3], 0, s[8:9]
	global_load_dword v108, v[2:3], off
	global_load_dword v109, v[2:3], off offset:1024
	global_load_dword v110, v[2:3], off offset:2048
	global_load_dword v111, v[2:3], off offset:3072
	v_lshl_add_u64 v[2:3], v[2:3], 0, s[8:9]
	global_load_dword v112, v[2:3], off
	global_load_dword v113, v[2:3], off offset:1024
	global_load_dword v114, v[2:3], off offset:2048
	global_load_dword v115, v[2:3], off offset:3072
	v_lshl_add_u64 v[2:3], v[2:3], 0, s[8:9]
	global_load_dwordx4 v[116:119], v[0:1], off offset:128
	global_load_dwordx4 v[120:123], v[0:1], off offset:144
	global_load_dwordx4 v[124:127], v[0:1], off offset:160
	global_load_dwordx4 v[128:131], v[0:1], off offset:176
	global_load_dword v132, v[2:3], off
	global_load_dword v133, v[2:3], off offset:1024
	global_load_dword v134, v[2:3], off offset:2048
	global_load_dword v135, v[2:3], off offset:3072
	v_lshl_add_u64 v[2:3], v[2:3], 0, s[8:9]
	global_load_dword v136, v[2:3], off
	global_load_dword v137, v[2:3], off offset:1024
	global_load_dword v138, v[2:3], off offset:2048
	global_load_dword v139, v[2:3], off offset:3072
	v_lshl_add_u64 v[2:3], v[2:3], 0, s[8:9]
	global_load_dword v140, v[2:3], off
	global_load_dword v141, v[2:3], off offset:1024
	global_load_dword v142, v[2:3], off offset:2048
	global_load_dword v143, v[2:3], off offset:3072
	v_lshl_add_u64 v[2:3], v[2:3], 0, s[8:9]
	global_load_dword v144, v[2:3], off
	global_load_dword v145, v[2:3], off offset:1024
	global_load_dword v146, v[2:3], off offset:2048
	global_load_dword v147, v[2:3], off offset:3072
	v_lshl_add_u64 v[2:3], v[2:3], 0, s[8:9]
	global_load_dwordx4 v[210:213], v[0:1], off offset:192
	global_load_dwordx4 v[214:217], v[0:1], off offset:208
	global_load_dwordx4 v[218:221], v[0:1], off offset:224
	global_load_dwordx4 v[222:225], v[0:1], off offset:240
	global_load_dword v226, v[2:3], off
	global_load_dword v227, v[2:3], off offset:1024
	global_load_dword v228, v[2:3], off offset:2048
	global_load_dword v229, v[2:3], off offset:3072
	v_lshl_add_u64 v[2:3], v[2:3], 0, s[8:9]
	global_load_dword v230, v[2:3], off
	global_load_dword v231, v[2:3], off offset:1024
	global_load_dword v232, v[2:3], off offset:2048
	global_load_dword v233, v[2:3], off offset:3072
	v_lshl_add_u64 v[2:3], v[2:3], 0, s[8:9]
	global_load_dword v234, v[2:3], off
	global_load_dword v235, v[2:3], off offset:1024
	global_load_dword v236, v[2:3], off offset:2048
	global_load_dword v237, v[2:3], off offset:3072
	v_lshl_add_u64 v[2:3], v[2:3], 0, s[8:9]
	global_load_dword v238, v[2:3], off
	global_load_dword v239, v[2:3], off offset:1024
	global_load_dword v240, v[2:3], off offset:2048
	global_load_dword v241, v[2:3], off offset:3072
	v_lshl_add_u64 v[2:3], v[2:3], 0, s[8:9]
	s_waitcnt vmcnt(60)
	v_fmac_f32_e32 v8, v22, v38
	v_fmac_f32_e32 v8, v23, v39
	v_fmac_f32_e32 v8, v24, v40
	v_fmac_f32_e32 v8, v25, v41
	v_fmac_f32_e32 v8, v26, v42
	v_fmac_f32_e32 v8, v27, v43
	v_fmac_f32_e32 v8, v28, v44
	v_fmac_f32_e32 v8, v29, v45
	v_fmac_f32_e32 v8, v30, v46
	v_fmac_f32_e32 v8, v31, v47
	v_fmac_f32_e32 v8, v32, v48
	v_fmac_f32_e32 v8, v33, v49
	v_fmac_f32_e32 v8, v34, v50
	v_fmac_f32_e32 v8, v35, v51
	v_fmac_f32_e32 v8, v36, v52
	v_fmac_f32_e32 v8, v37, v53
	global_load_dwordx4 v[22:25], v[0:1], off offset:256
	global_load_dwordx4 v[26:29], v[0:1], off offset:272
	global_load_dwordx4 v[30:33], v[0:1], off offset:288
	global_load_dwordx4 v[34:37], v[0:1], off offset:304
	global_load_dword v38, v[2:3], off
	global_load_dword v39, v[2:3], off offset:1024
	global_load_dword v40, v[2:3], off offset:2048
	global_load_dword v41, v[2:3], off offset:3072
	v_lshl_add_u64 v[2:3], v[2:3], 0, s[8:9]
	global_load_dword v42, v[2:3], off
	global_load_dword v43, v[2:3], off offset:1024
	global_load_dword v44, v[2:3], off offset:2048
	global_load_dword v45, v[2:3], off offset:3072
	v_lshl_add_u64 v[2:3], v[2:3], 0, s[8:9]
	global_load_dword v46, v[2:3], off
	global_load_dword v47, v[2:3], off offset:1024
	global_load_dword v48, v[2:3], off offset:2048
	global_load_dword v49, v[2:3], off offset:3072
	v_lshl_add_u64 v[2:3], v[2:3], 0, s[8:9]
	global_load_dword v50, v[2:3], off
	global_load_dword v51, v[2:3], off offset:1024
	global_load_dword v52, v[2:3], off offset:2048
	global_load_dword v53, v[2:3], off offset:3072
	v_lshl_add_u64 v[2:3], v[2:3], 0, s[8:9]
	s_waitcnt vmcnt(60)
	v_fmac_f32_e32 v8, v84, v100
	v_fmac_f32_e32 v8, v85, v101
	v_fmac_f32_e32 v8, v86, v102
	v_fmac_f32_e32 v8, v87, v103
	v_fmac_f32_e32 v8, v88, v104
	v_fmac_f32_e32 v8, v89, v105
	v_fmac_f32_e32 v8, v90, v106
	v_fmac_f32_e32 v8, v91, v107
	v_fmac_f32_e32 v8, v92, v108
	v_fmac_f32_e32 v8, v93, v109
	v_fmac_f32_e32 v8, v94, v110
	v_fmac_f32_e32 v8, v95, v111
	v_fmac_f32_e32 v8, v96, v112
	v_fmac_f32_e32 v8, v97, v113
	v_fmac_f32_e32 v8, v98, v114
	v_fmac_f32_e32 v8, v99, v115
	global_load_dwordx4 v[84:87], v[0:1], off offset:320
	global_load_dwordx4 v[88:91], v[0:1], off offset:336
	global_load_dwordx4 v[92:95], v[0:1], off offset:352
	global_load_dwordx4 v[96:99], v[0:1], off offset:368
	global_load_dword v100, v[2:3], off
	global_load_dword v101, v[2:3], off offset:1024
	global_load_dword v102, v[2:3], off offset:2048
	global_load_dword v103, v[2:3], off offset:3072
	v_lshl_add_u64 v[2:3], v[2:3], 0, s[8:9]
	global_load_dword v104, v[2:3], off
	global_load_dword v105, v[2:3], off offset:1024
	global_load_dword v106, v[2:3], off offset:2048
	global_load_dword v107, v[2:3], off offset:3072
	v_lshl_add_u64 v[2:3], v[2:3], 0, s[8:9]
	global_load_dword v108, v[2:3], off
	global_load_dword v109, v[2:3], off offset:1024
	global_load_dword v110, v[2:3], off offset:2048
	global_load_dword v111, v[2:3], off offset:3072
	v_lshl_add_u64 v[2:3], v[2:3], 0, s[8:9]
	global_load_dword v112, v[2:3], off
	global_load_dword v113, v[2:3], off offset:1024
	global_load_dword v114, v[2:3], off offset:2048
	global_load_dword v115, v[2:3], off offset:3072
	v_lshl_add_u64 v[2:3], v[2:3], 0, s[8:9]
	s_waitcnt vmcnt(60)
	v_fmac_f32_e32 v8, v116, v132
	v_fmac_f32_e32 v8, v117, v133
	v_fmac_f32_e32 v8, v118, v134
	v_fmac_f32_e32 v8, v119, v135
	v_fmac_f32_e32 v8, v120, v136
	v_fmac_f32_e32 v8, v121, v137
	v_fmac_f32_e32 v8, v122, v138
	v_fmac_f32_e32 v8, v123, v139
	v_fmac_f32_e32 v8, v124, v140
	v_fmac_f32_e32 v8, v125, v141
	v_fmac_f32_e32 v8, v126, v142
	v_fmac_f32_e32 v8, v127, v143
	v_fmac_f32_e32 v8, v128, v144
	v_fmac_f32_e32 v8, v129, v145
	v_fmac_f32_e32 v8, v130, v146
	v_fmac_f32_e32 v8, v131, v147
	global_load_dwordx4 v[116:119], v[0:1], off offset:384
	global_load_dwordx4 v[120:123], v[0:1], off offset:400
	global_load_dwordx4 v[124:127], v[0:1], off offset:416
	global_load_dwordx4 v[128:131], v[0:1], off offset:432
	global_load_dword v132, v[2:3], off
	global_load_dword v133, v[2:3], off offset:1024
	global_load_dword v134, v[2:3], off offset:2048
	global_load_dword v135, v[2:3], off offset:3072
	v_lshl_add_u64 v[2:3], v[2:3], 0, s[8:9]
	global_load_dword v136, v[2:3], off
	global_load_dword v137, v[2:3], off offset:1024
	global_load_dword v138, v[2:3], off offset:2048
	global_load_dword v139, v[2:3], off offset:3072
	v_lshl_add_u64 v[2:3], v[2:3], 0, s[8:9]
	global_load_dword v140, v[2:3], off
	global_load_dword v141, v[2:3], off offset:1024
	global_load_dword v142, v[2:3], off offset:2048
	global_load_dword v143, v[2:3], off offset:3072
	v_lshl_add_u64 v[2:3], v[2:3], 0, s[8:9]
	global_load_dword v144, v[2:3], off
	global_load_dword v145, v[2:3], off offset:1024
	global_load_dword v146, v[2:3], off offset:2048
	global_load_dword v147, v[2:3], off offset:3072
	v_lshl_add_u64 v[2:3], v[2:3], 0, s[8:9]
	s_waitcnt vmcnt(60)
	v_fmac_f32_e32 v8, v210, v226
	v_fmac_f32_e32 v8, v211, v227
	v_fmac_f32_e32 v8, v212, v228
	v_fmac_f32_e32 v8, v213, v229
	v_fmac_f32_e32 v8, v214, v230
	v_fmac_f32_e32 v8, v215, v231
	v_fmac_f32_e32 v8, v216, v232
	v_fmac_f32_e32 v8, v217, v233
	v_fmac_f32_e32 v8, v218, v234
	v_fmac_f32_e32 v8, v219, v235
	v_fmac_f32_e32 v8, v220, v236
	v_fmac_f32_e32 v8, v221, v237
	v_fmac_f32_e32 v8, v222, v238
	v_fmac_f32_e32 v8, v223, v239
	v_fmac_f32_e32 v8, v224, v240
	v_fmac_f32_e32 v8, v225, v241
	global_load_dwordx4 v[210:213], v[0:1], off offset:448
	global_load_dwordx4 v[214:217], v[0:1], off offset:464
	global_load_dwordx4 v[218:221], v[0:1], off offset:480
	global_load_dwordx4 v[222:225], v[0:1], off offset:496
	global_load_dword v226, v[2:3], off
	global_load_dword v227, v[2:3], off offset:1024
	global_load_dword v228, v[2:3], off offset:2048
	global_load_dword v229, v[2:3], off offset:3072
	v_lshl_add_u64 v[2:3], v[2:3], 0, s[8:9]
	global_load_dword v230, v[2:3], off
	global_load_dword v231, v[2:3], off offset:1024
	global_load_dword v232, v[2:3], off offset:2048
	global_load_dword v233, v[2:3], off offset:3072
	v_lshl_add_u64 v[2:3], v[2:3], 0, s[8:9]
	global_load_dword v234, v[2:3], off
	global_load_dword v235, v[2:3], off offset:1024
	global_load_dword v236, v[2:3], off offset:2048
	global_load_dword v237, v[2:3], off offset:3072
	v_lshl_add_u64 v[2:3], v[2:3], 0, s[8:9]
	global_load_dword v238, v[2:3], off
	global_load_dword v239, v[2:3], off offset:1024
	global_load_dword v240, v[2:3], off offset:2048
	global_load_dword v241, v[2:3], off offset:3072
	v_lshl_add_u64 v[2:3], v[2:3], 0, s[8:9]
	s_waitcnt vmcnt(60)
	v_fmac_f32_e32 v8, v22, v38
	v_fmac_f32_e32 v8, v23, v39
	v_fmac_f32_e32 v8, v24, v40
	v_fmac_f32_e32 v8, v25, v41
	v_fmac_f32_e32 v8, v26, v42
	v_fmac_f32_e32 v8, v27, v43
	v_fmac_f32_e32 v8, v28, v44
	v_fmac_f32_e32 v8, v29, v45
	v_fmac_f32_e32 v8, v30, v46
	v_fmac_f32_e32 v8, v31, v47
	v_fmac_f32_e32 v8, v32, v48
	v_fmac_f32_e32 v8, v33, v49
	v_fmac_f32_e32 v8, v34, v50
	v_fmac_f32_e32 v8, v35, v51
	v_fmac_f32_e32 v8, v36, v52
	v_fmac_f32_e32 v8, v37, v53
	global_load_dwordx4 v[22:25], v[0:1], off offset:512
	global_load_dwordx4 v[26:29], v[0:1], off offset:528
	global_load_dwordx4 v[30:33], v[0:1], off offset:544
	global_load_dwordx4 v[34:37], v[0:1], off offset:560
	global_load_dword v38, v[2:3], off
	global_load_dword v39, v[2:3], off offset:1024
	global_load_dword v40, v[2:3], off offset:2048
	global_load_dword v41, v[2:3], off offset:3072
	v_lshl_add_u64 v[2:3], v[2:3], 0, s[8:9]
	global_load_dword v42, v[2:3], off
	global_load_dword v43, v[2:3], off offset:1024
	global_load_dword v44, v[2:3], off offset:2048
	global_load_dword v45, v[2:3], off offset:3072
	v_lshl_add_u64 v[2:3], v[2:3], 0, s[8:9]
	global_load_dword v46, v[2:3], off
	global_load_dword v47, v[2:3], off offset:1024
	global_load_dword v48, v[2:3], off offset:2048
	global_load_dword v49, v[2:3], off offset:3072
	v_lshl_add_u64 v[2:3], v[2:3], 0, s[8:9]
	global_load_dword v50, v[2:3], off
	global_load_dword v51, v[2:3], off offset:1024
	global_load_dword v52, v[2:3], off offset:2048
	global_load_dword v53, v[2:3], off offset:3072
	v_lshl_add_u64 v[2:3], v[2:3], 0, s[8:9]
	s_waitcnt vmcnt(60)
	v_fmac_f32_e32 v8, v84, v100
	v_fmac_f32_e32 v8, v85, v101
	v_fmac_f32_e32 v8, v86, v102
	v_fmac_f32_e32 v8, v87, v103
	v_fmac_f32_e32 v8, v88, v104
	v_fmac_f32_e32 v8, v89, v105
	v_fmac_f32_e32 v8, v90, v106
	v_fmac_f32_e32 v8, v91, v107
	v_fmac_f32_e32 v8, v92, v108
	v_fmac_f32_e32 v8, v93, v109
	v_fmac_f32_e32 v8, v94, v110
	v_fmac_f32_e32 v8, v95, v111
	v_fmac_f32_e32 v8, v96, v112
	v_fmac_f32_e32 v8, v97, v113
	v_fmac_f32_e32 v8, v98, v114
	v_fmac_f32_e32 v8, v99, v115
	global_load_dwordx4 v[84:87], v[0:1], off offset:576
	global_load_dwordx4 v[88:91], v[0:1], off offset:592
	global_load_dwordx4 v[92:95], v[0:1], off offset:608
	global_load_dwordx4 v[96:99], v[0:1], off offset:624
	global_load_dword v100, v[2:3], off
	global_load_dword v101, v[2:3], off offset:1024
	global_load_dword v102, v[2:3], off offset:2048
	global_load_dword v103, v[2:3], off offset:3072
	v_lshl_add_u64 v[2:3], v[2:3], 0, s[8:9]
	global_load_dword v104, v[2:3], off
	global_load_dword v105, v[2:3], off offset:1024
	global_load_dword v106, v[2:3], off offset:2048
	global_load_dword v107, v[2:3], off offset:3072
	v_lshl_add_u64 v[2:3], v[2:3], 0, s[8:9]
	global_load_dword v108, v[2:3], off
	global_load_dword v109, v[2:3], off offset:1024
	global_load_dword v110, v[2:3], off offset:2048
	global_load_dword v111, v[2:3], off offset:3072
	v_lshl_add_u64 v[2:3], v[2:3], 0, s[8:9]
	global_load_dword v112, v[2:3], off
	global_load_dword v113, v[2:3], off offset:1024
	global_load_dword v114, v[2:3], off offset:2048
	global_load_dword v115, v[2:3], off offset:3072
	v_lshl_add_u64 v[2:3], v[2:3], 0, s[8:9]
	s_waitcnt vmcnt(60)
	v_fmac_f32_e32 v8, v116, v132
	v_fmac_f32_e32 v8, v117, v133
	v_fmac_f32_e32 v8, v118, v134
	v_fmac_f32_e32 v8, v119, v135
	v_fmac_f32_e32 v8, v120, v136
	v_fmac_f32_e32 v8, v121, v137
	v_fmac_f32_e32 v8, v122, v138
	v_fmac_f32_e32 v8, v123, v139
	v_fmac_f32_e32 v8, v124, v140
	v_fmac_f32_e32 v8, v125, v141
	v_fmac_f32_e32 v8, v126, v142
	v_fmac_f32_e32 v8, v127, v143
	v_fmac_f32_e32 v8, v128, v144
	v_fmac_f32_e32 v8, v129, v145
	v_fmac_f32_e32 v8, v130, v146
	v_fmac_f32_e32 v8, v131, v147
	global_load_dwordx4 v[116:119], v[0:1], off offset:640
	global_load_dwordx4 v[120:123], v[0:1], off offset:656
	global_load_dwordx4 v[124:127], v[0:1], off offset:672
	global_load_dwordx4 v[128:131], v[0:1], off offset:688
	global_load_dword v132, v[2:3], off
	global_load_dword v133, v[2:3], off offset:1024
	global_load_dword v134, v[2:3], off offset:2048
	global_load_dword v135, v[2:3], off offset:3072
	v_lshl_add_u64 v[2:3], v[2:3], 0, s[8:9]
	global_load_dword v136, v[2:3], off
	global_load_dword v137, v[2:3], off offset:1024
	global_load_dword v138, v[2:3], off offset:2048
	global_load_dword v139, v[2:3], off offset:3072
	v_lshl_add_u64 v[2:3], v[2:3], 0, s[8:9]
	global_load_dword v140, v[2:3], off
	global_load_dword v141, v[2:3], off offset:1024
	global_load_dword v142, v[2:3], off offset:2048
	global_load_dword v143, v[2:3], off offset:3072
	v_lshl_add_u64 v[2:3], v[2:3], 0, s[8:9]
	global_load_dword v144, v[2:3], off
	global_load_dword v145, v[2:3], off offset:1024
	global_load_dword v146, v[2:3], off offset:2048
	global_load_dword v147, v[2:3], off offset:3072
	v_lshl_add_u64 v[2:3], v[2:3], 0, s[8:9]
	s_waitcnt vmcnt(60)
	v_fmac_f32_e32 v8, v210, v226
	v_fmac_f32_e32 v8, v211, v227
	v_fmac_f32_e32 v8, v212, v228
	v_fmac_f32_e32 v8, v213, v229
	v_fmac_f32_e32 v8, v214, v230
	v_fmac_f32_e32 v8, v215, v231
	v_fmac_f32_e32 v8, v216, v232
	v_fmac_f32_e32 v8, v217, v233
	v_fmac_f32_e32 v8, v218, v234
	v_fmac_f32_e32 v8, v219, v235
	v_fmac_f32_e32 v8, v220, v236
	v_fmac_f32_e32 v8, v221, v237
	v_fmac_f32_e32 v8, v222, v238
	v_fmac_f32_e32 v8, v223, v239
	v_fmac_f32_e32 v8, v224, v240
	v_fmac_f32_e32 v8, v225, v241
	global_load_dwordx4 v[210:213], v[0:1], off offset:704
	global_load_dwordx4 v[214:217], v[0:1], off offset:720
	global_load_dwordx4 v[218:221], v[0:1], off offset:736
	global_load_dwordx4 v[222:225], v[0:1], off offset:752
	global_load_dword v226, v[2:3], off
	global_load_dword v227, v[2:3], off offset:1024
	global_load_dword v228, v[2:3], off offset:2048
	global_load_dword v229, v[2:3], off offset:3072
	v_lshl_add_u64 v[2:3], v[2:3], 0, s[8:9]
	global_load_dword v230, v[2:3], off
	global_load_dword v231, v[2:3], off offset:1024
	global_load_dword v232, v[2:3], off offset:2048
	global_load_dword v233, v[2:3], off offset:3072
	v_lshl_add_u64 v[2:3], v[2:3], 0, s[8:9]
	global_load_dword v234, v[2:3], off
	global_load_dword v235, v[2:3], off offset:1024
	global_load_dword v236, v[2:3], off offset:2048
	global_load_dword v237, v[2:3], off offset:3072
	v_lshl_add_u64 v[2:3], v[2:3], 0, s[8:9]
	global_load_dword v238, v[2:3], off
	global_load_dword v239, v[2:3], off offset:1024
	global_load_dword v240, v[2:3], off offset:2048
	global_load_dword v241, v[2:3], off offset:3072
	v_lshl_add_u64 v[2:3], v[2:3], 0, s[8:9]
	s_waitcnt vmcnt(60)
	v_fmac_f32_e32 v8, v22, v38
	v_fmac_f32_e32 v8, v23, v39
	v_fmac_f32_e32 v8, v24, v40
	v_fmac_f32_e32 v8, v25, v41
	v_fmac_f32_e32 v8, v26, v42
	v_fmac_f32_e32 v8, v27, v43
	v_fmac_f32_e32 v8, v28, v44
	v_fmac_f32_e32 v8, v29, v45
	v_fmac_f32_e32 v8, v30, v46
	v_fmac_f32_e32 v8, v31, v47
	v_fmac_f32_e32 v8, v32, v48
	v_fmac_f32_e32 v8, v33, v49
	v_fmac_f32_e32 v8, v34, v50
	v_fmac_f32_e32 v8, v35, v51
	v_fmac_f32_e32 v8, v36, v52
	v_fmac_f32_e32 v8, v37, v53
	global_load_dwordx4 v[22:25], v[0:1], off offset:768
	global_load_dwordx4 v[26:29], v[0:1], off offset:784
	global_load_dwordx4 v[30:33], v[0:1], off offset:800
	global_load_dwordx4 v[34:37], v[0:1], off offset:816
	global_load_dword v38, v[2:3], off
	global_load_dword v39, v[2:3], off offset:1024
	global_load_dword v40, v[2:3], off offset:2048
	global_load_dword v41, v[2:3], off offset:3072
	v_lshl_add_u64 v[2:3], v[2:3], 0, s[8:9]
	global_load_dword v42, v[2:3], off
	global_load_dword v43, v[2:3], off offset:1024
	global_load_dword v44, v[2:3], off offset:2048
	global_load_dword v45, v[2:3], off offset:3072
	v_lshl_add_u64 v[2:3], v[2:3], 0, s[8:9]
	global_load_dword v46, v[2:3], off
	global_load_dword v47, v[2:3], off offset:1024
	global_load_dword v48, v[2:3], off offset:2048
	global_load_dword v49, v[2:3], off offset:3072
	v_lshl_add_u64 v[2:3], v[2:3], 0, s[8:9]
	global_load_dword v50, v[2:3], off
	global_load_dword v51, v[2:3], off offset:1024
	global_load_dword v52, v[2:3], off offset:2048
	global_load_dword v53, v[2:3], off offset:3072
	v_lshl_add_u64 v[2:3], v[2:3], 0, s[8:9]
	s_waitcnt vmcnt(60)
	v_fmac_f32_e32 v8, v84, v100
	v_fmac_f32_e32 v8, v85, v101
	v_fmac_f32_e32 v8, v86, v102
	v_fmac_f32_e32 v8, v87, v103
	v_fmac_f32_e32 v8, v88, v104
	v_fmac_f32_e32 v8, v89, v105
	v_fmac_f32_e32 v8, v90, v106
	v_fmac_f32_e32 v8, v91, v107
	v_fmac_f32_e32 v8, v92, v108
	v_fmac_f32_e32 v8, v93, v109
	v_fmac_f32_e32 v8, v94, v110
	v_fmac_f32_e32 v8, v95, v111
	v_fmac_f32_e32 v8, v96, v112
	v_fmac_f32_e32 v8, v97, v113
	v_fmac_f32_e32 v8, v98, v114
	v_fmac_f32_e32 v8, v99, v115
	global_load_dwordx4 v[84:87], v[0:1], off offset:832
	global_load_dwordx4 v[88:91], v[0:1], off offset:848
	global_load_dwordx4 v[92:95], v[0:1], off offset:864
	global_load_dwordx4 v[96:99], v[0:1], off offset:880
	global_load_dword v100, v[2:3], off
	global_load_dword v101, v[2:3], off offset:1024
	global_load_dword v102, v[2:3], off offset:2048
	global_load_dword v103, v[2:3], off offset:3072
	v_lshl_add_u64 v[2:3], v[2:3], 0, s[8:9]
	global_load_dword v104, v[2:3], off
	global_load_dword v105, v[2:3], off offset:1024
	global_load_dword v106, v[2:3], off offset:2048
	global_load_dword v107, v[2:3], off offset:3072
	v_lshl_add_u64 v[2:3], v[2:3], 0, s[8:9]
	global_load_dword v108, v[2:3], off
	global_load_dword v109, v[2:3], off offset:1024
	global_load_dword v110, v[2:3], off offset:2048
	global_load_dword v111, v[2:3], off offset:3072
	v_lshl_add_u64 v[2:3], v[2:3], 0, s[8:9]
	global_load_dword v112, v[2:3], off
	global_load_dword v113, v[2:3], off offset:1024
	global_load_dword v114, v[2:3], off offset:2048
	global_load_dword v115, v[2:3], off offset:3072
	v_lshl_add_u64 v[2:3], v[2:3], 0, s[8:9]
	s_waitcnt vmcnt(60)
	v_fmac_f32_e32 v8, v116, v132
	v_fmac_f32_e32 v8, v117, v133
	v_fmac_f32_e32 v8, v118, v134
	v_fmac_f32_e32 v8, v119, v135
	v_fmac_f32_e32 v8, v120, v136
	v_fmac_f32_e32 v8, v121, v137
	v_fmac_f32_e32 v8, v122, v138
	v_fmac_f32_e32 v8, v123, v139
	v_fmac_f32_e32 v8, v124, v140
	v_fmac_f32_e32 v8, v125, v141
	v_fmac_f32_e32 v8, v126, v142
	v_fmac_f32_e32 v8, v127, v143
	v_fmac_f32_e32 v8, v128, v144
	v_fmac_f32_e32 v8, v129, v145
	v_fmac_f32_e32 v8, v130, v146
	v_fmac_f32_e32 v8, v131, v147
	global_load_dwordx4 v[116:119], v[0:1], off offset:896
	global_load_dwordx4 v[120:123], v[0:1], off offset:912
	global_load_dwordx4 v[124:127], v[0:1], off offset:928
	global_load_dwordx4 v[128:131], v[0:1], off offset:944
	global_load_dword v132, v[2:3], off
	global_load_dword v133, v[2:3], off offset:1024
	global_load_dword v134, v[2:3], off offset:2048
	global_load_dword v135, v[2:3], off offset:3072
	v_lshl_add_u64 v[2:3], v[2:3], 0, s[8:9]
	global_load_dword v136, v[2:3], off
	global_load_dword v137, v[2:3], off offset:1024
	global_load_dword v138, v[2:3], off offset:2048
	global_load_dword v139, v[2:3], off offset:3072
	v_lshl_add_u64 v[2:3], v[2:3], 0, s[8:9]
	global_load_dword v140, v[2:3], off
	global_load_dword v141, v[2:3], off offset:1024
	global_load_dword v142, v[2:3], off offset:2048
	global_load_dword v143, v[2:3], off offset:3072
	v_lshl_add_u64 v[2:3], v[2:3], 0, s[8:9]
	global_load_dword v144, v[2:3], off
	global_load_dword v145, v[2:3], off offset:1024
	global_load_dword v146, v[2:3], off offset:2048
	global_load_dword v147, v[2:3], off offset:3072
	v_lshl_add_u64 v[2:3], v[2:3], 0, s[8:9]
	s_waitcnt vmcnt(60)
	v_fmac_f32_e32 v8, v210, v226
	v_fmac_f32_e32 v8, v211, v227
	v_fmac_f32_e32 v8, v212, v228
	v_fmac_f32_e32 v8, v213, v229
	v_fmac_f32_e32 v8, v214, v230
	v_fmac_f32_e32 v8, v215, v231
	v_fmac_f32_e32 v8, v216, v232
	v_fmac_f32_e32 v8, v217, v233
	v_fmac_f32_e32 v8, v218, v234
	v_fmac_f32_e32 v8, v219, v235
	v_fmac_f32_e32 v8, v220, v236
	v_fmac_f32_e32 v8, v221, v237
	v_fmac_f32_e32 v8, v222, v238
	v_fmac_f32_e32 v8, v223, v239
	v_fmac_f32_e32 v8, v224, v240
	v_fmac_f32_e32 v8, v225, v241
	global_load_dwordx4 v[210:213], v[0:1], off offset:960
	global_load_dwordx4 v[214:217], v[0:1], off offset:976
	global_load_dwordx4 v[218:221], v[0:1], off offset:992
	global_load_dwordx4 v[222:225], v[0:1], off offset:1008
	global_load_dword v226, v[2:3], off
	global_load_dword v227, v[2:3], off offset:1024
	global_load_dword v228, v[2:3], off offset:2048
	global_load_dword v229, v[2:3], off offset:3072
	v_lshl_add_u64 v[2:3], v[2:3], 0, s[8:9]
	global_load_dword v230, v[2:3], off
	global_load_dword v231, v[2:3], off offset:1024
	global_load_dword v232, v[2:3], off offset:2048
	global_load_dword v233, v[2:3], off offset:3072
	v_lshl_add_u64 v[2:3], v[2:3], 0, s[8:9]
	global_load_dword v234, v[2:3], off
	global_load_dword v235, v[2:3], off offset:1024
	global_load_dword v236, v[2:3], off offset:2048
	global_load_dword v237, v[2:3], off offset:3072
	v_lshl_add_u64 v[2:3], v[2:3], 0, s[8:9]
	global_load_dword v238, v[2:3], off
	global_load_dword v239, v[2:3], off offset:1024
	global_load_dword v240, v[2:3], off offset:2048
	global_load_dword v241, v[2:3], off offset:3072
	v_lshl_add_u64 v[2:3], v[2:3], 0, s[8:9]
	s_waitcnt vmcnt(60)
	v_fmac_f32_e32 v8, v22, v38
	v_fmac_f32_e32 v8, v23, v39
	v_fmac_f32_e32 v8, v24, v40
	v_fmac_f32_e32 v8, v25, v41
	v_fmac_f32_e32 v8, v26, v42
	v_fmac_f32_e32 v8, v27, v43
	v_fmac_f32_e32 v8, v28, v44
	v_fmac_f32_e32 v8, v29, v45
	v_fmac_f32_e32 v8, v30, v46
	v_fmac_f32_e32 v8, v31, v47
	v_fmac_f32_e32 v8, v32, v48
	v_fmac_f32_e32 v8, v33, v49
	v_fmac_f32_e32 v8, v34, v50
	v_fmac_f32_e32 v8, v35, v51
	v_fmac_f32_e32 v8, v36, v52
	v_fmac_f32_e32 v8, v37, v53
	s_waitcnt vmcnt(40)
	v_fmac_f32_e32 v8, v84, v100
	v_fmac_f32_e32 v8, v85, v101
	v_fmac_f32_e32 v8, v86, v102
	v_fmac_f32_e32 v8, v87, v103
	v_fmac_f32_e32 v8, v88, v104
	v_fmac_f32_e32 v8, v89, v105
	v_fmac_f32_e32 v8, v90, v106
	v_fmac_f32_e32 v8, v91, v107
	v_fmac_f32_e32 v8, v92, v108
	v_fmac_f32_e32 v8, v93, v109
	v_fmac_f32_e32 v8, v94, v110
	v_fmac_f32_e32 v8, v95, v111
	v_fmac_f32_e32 v8, v96, v112
	v_fmac_f32_e32 v8, v97, v113
	v_fmac_f32_e32 v8, v98, v114
	v_fmac_f32_e32 v8, v99, v115
	s_waitcnt vmcnt(20)
	v_fmac_f32_e32 v8, v116, v132
	v_fmac_f32_e32 v8, v117, v133
	v_fmac_f32_e32 v8, v118, v134
	v_fmac_f32_e32 v8, v119, v135
	v_fmac_f32_e32 v8, v120, v136
	v_fmac_f32_e32 v8, v121, v137
	v_fmac_f32_e32 v8, v122, v138
	v_fmac_f32_e32 v8, v123, v139
	v_fmac_f32_e32 v8, v124, v140
	v_fmac_f32_e32 v8, v125, v141
	v_fmac_f32_e32 v8, v126, v142
	v_fmac_f32_e32 v8, v127, v143
	v_fmac_f32_e32 v8, v128, v144
	v_fmac_f32_e32 v8, v129, v145
	v_fmac_f32_e32 v8, v130, v146
	v_fmac_f32_e32 v8, v131, v147
	s_waitcnt vmcnt(0)
	v_fmac_f32_e32 v8, v210, v226
	v_fmac_f32_e32 v8, v211, v227
	v_fmac_f32_e32 v8, v212, v228
	v_fmac_f32_e32 v8, v213, v229
	v_fmac_f32_e32 v8, v214, v230
	v_fmac_f32_e32 v8, v215, v231
	v_fmac_f32_e32 v8, v216, v232
	v_fmac_f32_e32 v8, v217, v233
	v_fmac_f32_e32 v8, v218, v234
	v_fmac_f32_e32 v8, v219, v235
	v_fmac_f32_e32 v8, v220, v236
	v_fmac_f32_e32 v8, v221, v237
	v_fmac_f32_e32 v8, v222, v238
	v_fmac_f32_e32 v8, v223, v239
	v_fmac_f32_e32 v8, v224, v240
	v_fmac_f32_e32 v8, v225, v241
	s_or_b64 exec, exec, s[6:7]
	v_lshlrev_b32_e32 v0, 2, v20
	v_cmp_gt_i32_e32 vcc, 32, v20
	ds_write_b32 v0, v8
	s_waitcnt lgkmcnt(0)
	s_barrier
	s_and_saveexec_b64 s[6:7], vcc
	s_cbranch_execz .LBB0_280
	ds_read2_b32 v[2:3], v0 offset1:32
	v_readlane_b32 s5, v251, 46
	s_waitcnt lgkmcnt(0)
	v_add_f32_e32 v1, v3, v2
	ds_read2_b32 v[2:3], v0 offset0:64 offset1:96
	s_waitcnt lgkmcnt(0)
	v_add_f32_e32 v1, v1, v2
	v_add_f32_e32 v1, v1, v3
	ds_read2_b32 v[2:3], v0 offset0:128 offset1:160
	s_waitcnt lgkmcnt(0)
	v_add_f32_e32 v1, v1, v2
	v_add_f32_e32 v2, v1, v3
	ds_read2_b32 v[0:1], v0 offset0:192 offset1:224
	s_waitcnt lgkmcnt(0)
	v_add_f32_e32 v0, v2, v0
	v_add_f32_e32 v2, v0, v1
	v_add_u32_e32 v0, s5, v20
	v_ashrrev_i32_e32 v1, 31, v0
	v_lshl_add_u64 v[0:1], v[0:1], 2, s[0:1]
	v_add_co_u32_e32 v0, vcc, 0xe280000, v0
	s_nop 1
	v_addc_co_u32_e32 v1, vcc, 0, v1, vcc
	global_store_dword v[0:1], v2, off
